# grid barrier: non-leader workgroups poll the cross-XCD release generation directly (one hop less on release), on top of the combination
# speedup vs baseline: 1.0129x; 1.0071x over previous
; __device__ __forceinline__ unsigned xb_ld(unsigned* p)              { return __hip_atomic_load(p, __ATOMIC_RELAXED, __HIP_MEMORY_SCOPE_AGENT); }
; __device__ __forceinline__ unsigned xb_add(unsigned* p, unsigned v) { return __hip_atomic_fetch_add(p, v, __ATOMIC_RELAXED, __HIP_MEMORY_SCOPE_AGENT); }
; #define XB_SPIN(cond, bar) do { unsigned _sp = 0; while (cond) { __builtin_amdgcn_s_sleep(1); \
;     if ((++_sp & 255u) == 0u) { if (xb_ld(&(bar)[XB_TMO])) break; if (_sp > XB_SPIN_CAP) { atomicAdd(&(bar)[XB_TMO], 1u); break; } } } } while (0)
; __device__ __forceinline__ void xcd_barrier(const XcdBarrier& b) {
;     ...
;         const unsigned old = xb_add(&bar[XB_XSUB(b.x)], 1u);
;         const unsigned gen = old / nloc;
;         if (old + 1u == (gen + 1u) * nloc) {
;             __builtin_amdgcn_fence(__ATOMIC_RELEASE, "agent");
;             asm volatile("s_waitcnt vmcnt(0)" ::: "memory");
;             const unsigned og = xb_add(&bar[XB_TOP], 1u);
;             const unsigned tg = og / nx;
;             if (og + 1u == (tg + 1u) * nx) xb_add(&bar[XB_TOPGEN], 1u);
;             else XB_SPIN(xb_ld(&bar[XB_TOPGEN]) == tg, bar);
;             __builtin_amdgcn_fence(__ATOMIC_ACQUIRE, "agent");
;             xb_add(&bar[XB_XGEN(b.x)], 1u);
;             asm volatile("s_waitcnt vmcnt(0)" ::: "memory");
;         } else {
;             XB_SPIN(xb_ld(&bar[XB_XGEN(b.x)]) == gen, bar);
.LBB0_122:
	s_or_b64 exec, exec, s[12:13]
	v_cvt_f32_u32_e32 v4, v2
	s_waitcnt vmcnt(0)
	v_readfirstlane_b32 s3, v3
	v_sub_u32_e32 v3, 0, v2
	v_rcp_iflag_f32_e32 v4, v4
	v_add_u32_e32 v5, s3, v1
	v_mul_f32_e32 v4, 0x4f7ffffe, v4
	v_cvt_u32_f32_e32 v4, v4
	v_mul_lo_u32 v1, v3, v4
	v_mul_hi_u32 v1, v4, v1
	v_add_u32_e32 v1, v4, v1
	v_mul_hi_u32 v1, v5, v1
	v_mul_lo_u32 v3, v1, v2
	v_sub_u32_e32 v3, v5, v3
	v_add_u32_e32 v4, 1, v1
	v_cmp_ge_u32_e32 vcc, v3, v2
	s_nop 1
	v_cndmask_b32_e32 v1, v1, v4, vcc
	v_sub_u32_e32 v4, v3, v2
	v_cndmask_b32_e32 v3, v3, v4, vcc
	v_add_u32_e32 v4, 1, v1
	v_cmp_ge_u32_e32 vcc, v3, v2
	v_add_u32_e32 v3, 1, v5
	s_nop 0
	v_cndmask_b32_e32 v1, v1, v4, vcc
	v_mul_lo_u32 v4, v2, v1
	v_add_u32_e32 v2, v4, v2
	v_cmp_ne_u32_e32 vcc, v3, v2
	s_and_saveexec_b64 s[10:11], vcc
	s_xor_b64 s[10:11], exec, s[10:11]
	s_cbranch_execz .LBB0_136
	s_waitcnt lgkmcnt(0)
	v_mov_b32_e32 v0, 0xcb500
	global_load_dword v0, v0, s[6:7] sc1
	s_add_u32 s16, s6, 0xcb500
	s_addc_u32 s17, s7, 0
	s_waitcnt vmcnt(0)
	v_cmp_eq_u32_e32 vcc, v0, v1
	s_and_saveexec_b64 s[12:13], vcc
	s_cbranch_execz .LBB0_135
	s_add_u32 s14, s6, 0xc8200
	s_addc_u32 s15, s7, 0
	s_mov_b32 s3, 1
	s_mov_b64 s[18:19], 0
	v_mov_b32_e32 v0, 0
	s_branch .LBB0_126

; __device__ __forceinline__ unsigned xb_ld(unsigned* p)              { return __hip_atomic_load(p, __ATOMIC_RELAXED, __HIP_MEMORY_SCOPE_AGENT); }
; __device__ __forceinline__ unsigned xb_add(unsigned* p, unsigned v) { return __hip_atomic_fetch_add(p, v, __ATOMIC_RELAXED, __HIP_MEMORY_SCOPE_AGENT); }
; #define XB_SPIN(cond, bar) do { unsigned _sp = 0; while (cond) { __builtin_amdgcn_s_sleep(1); \
;     if ((++_sp & 255u) == 0u) { if (xb_ld(&(bar)[XB_TMO])) break; if (_sp > XB_SPIN_CAP) { atomicAdd(&(bar)[XB_TMO], 1u); break; } } } } while (0)
; __device__ __forceinline__ void xcd_barrier(const XcdBarrier& b) {
;     ...
;         const unsigned old = xb_add(&bar[XB_XSUB(b.x)], 1u);
;         const unsigned gen = old / nloc;
;         if (old + 1u == (gen + 1u) * nloc) {
;             __builtin_amdgcn_fence(__ATOMIC_RELEASE, "agent");
;             asm volatile("s_waitcnt vmcnt(0)" ::: "memory");
;             const unsigned og = xb_add(&bar[XB_TOP], 1u);
;             const unsigned tg = og / nx;
;             if (og + 1u == (tg + 1u) * nx) xb_add(&bar[XB_TOPGEN], 1u);
;             else XB_SPIN(xb_ld(&bar[XB_TOPGEN]) == tg, bar);
;             __builtin_amdgcn_fence(__ATOMIC_ACQUIRE, "agent");
;             xb_add(&bar[XB_XGEN(b.x)], 1u);
;             asm volatile("s_waitcnt vmcnt(0)" ::: "memory");
;         } else {
;             XB_SPIN(xb_ld(&bar[XB_XGEN(b.x)]) == gen, bar);
.LBB0_257:
	s_or_b64 exec, exec, s[12:13]
	v_cvt_f32_u32_e32 v4, v2
	s_waitcnt vmcnt(0)
	v_readfirstlane_b32 s3, v3
	v_sub_u32_e32 v3, 0, v2
	v_rcp_iflag_f32_e32 v4, v4
	v_add_u32_e32 v5, s3, v1
	v_mul_f32_e32 v4, 0x4f7ffffe, v4
	v_cvt_u32_f32_e32 v4, v4
	v_mul_lo_u32 v1, v3, v4
	v_mul_hi_u32 v1, v4, v1
	v_add_u32_e32 v1, v4, v1
	v_mul_hi_u32 v1, v5, v1
	v_mul_lo_u32 v3, v1, v2
	v_sub_u32_e32 v3, v5, v3
	v_add_u32_e32 v4, 1, v1
	v_cmp_ge_u32_e32 vcc, v3, v2
	s_nop 1
	v_cndmask_b32_e32 v1, v1, v4, vcc
	v_sub_u32_e32 v4, v3, v2
	v_cndmask_b32_e32 v3, v3, v4, vcc
	v_add_u32_e32 v4, 1, v1
	v_cmp_ge_u32_e32 vcc, v3, v2
	v_add_u32_e32 v3, 1, v5
	s_nop 0
	v_cndmask_b32_e32 v1, v1, v4, vcc
	v_mul_lo_u32 v4, v2, v1
	v_add_u32_e32 v2, v4, v2
	v_cmp_ne_u32_e32 vcc, v3, v2
	s_and_saveexec_b64 s[10:11], vcc
	s_xor_b64 s[10:11], exec, s[10:11]
	s_cbranch_execz .LBB0_271
	s_waitcnt lgkmcnt(0)
	v_mov_b32_e32 v0, 0xcb500
	global_load_dword v0, v0, s[6:7] sc1
	s_add_u32 s18, s6, 0xcb500
	s_addc_u32 s19, s7, 0
	s_waitcnt vmcnt(0)
	v_cmp_eq_u32_e32 vcc, v0, v1
	s_and_saveexec_b64 s[12:13], vcc
	s_cbranch_execz .LBB0_270
	s_add_u32 s14, s6, 0xc8200
	s_addc_u32 s15, s7, 0
	s_mov_b32 s3, 1
	s_mov_b64 s[20:21], 0
	v_mov_b32_e32 v0, 0
	s_branch .LBB0_261

; __device__ __forceinline__ unsigned xb_ld(unsigned* p)              { return __hip_atomic_load(p, __ATOMIC_RELAXED, __HIP_MEMORY_SCOPE_AGENT); }
; __device__ __forceinline__ unsigned xb_add(unsigned* p, unsigned v) { return __hip_atomic_fetch_add(p, v, __ATOMIC_RELAXED, __HIP_MEMORY_SCOPE_AGENT); }
; #define XB_SPIN(cond, bar) do { unsigned _sp = 0; while (cond) { __builtin_amdgcn_s_sleep(1); \
;     if ((++_sp & 255u) == 0u) { if (xb_ld(&(bar)[XB_TMO])) break; if (_sp > XB_SPIN_CAP) { atomicAdd(&(bar)[XB_TMO], 1u); break; } } } } while (0)
; __device__ __forceinline__ void xcd_barrier(const XcdBarrier& b) {
;     ...
;         const unsigned old = xb_add(&bar[XB_XSUB(b.x)], 1u);
;         const unsigned gen = old / nloc;
;         if (old + 1u == (gen + 1u) * nloc) {
;             __builtin_amdgcn_fence(__ATOMIC_RELEASE, "agent");
;             asm volatile("s_waitcnt vmcnt(0)" ::: "memory");
;             const unsigned og = xb_add(&bar[XB_TOP], 1u);
;             const unsigned tg = og / nx;
;             if (og + 1u == (tg + 1u) * nx) xb_add(&bar[XB_TOPGEN], 1u);
;             else XB_SPIN(xb_ld(&bar[XB_TOPGEN]) == tg, bar);
;             __builtin_amdgcn_fence(__ATOMIC_ACQUIRE, "agent");
;             xb_add(&bar[XB_XGEN(b.x)], 1u);
;             asm volatile("s_waitcnt vmcnt(0)" ::: "memory");
;         } else {
;             XB_SPIN(xb_ld(&bar[XB_XGEN(b.x)]) == gen, bar);
.LBB0_401:
	s_or_b64 exec, exec, s[12:13]
	v_cvt_f32_u32_e32 v4, v2
	s_waitcnt vmcnt(0)
	v_readfirstlane_b32 s3, v3
	v_sub_u32_e32 v3, 0, v2
	v_rcp_iflag_f32_e32 v4, v4
	v_add_u32_e32 v5, s3, v1
	v_mul_f32_e32 v4, 0x4f7ffffe, v4
	v_cvt_u32_f32_e32 v4, v4
	v_mul_lo_u32 v1, v3, v4
	v_mul_hi_u32 v1, v4, v1
	v_add_u32_e32 v1, v4, v1
	v_mul_hi_u32 v1, v5, v1
	v_mul_lo_u32 v3, v1, v2
	v_sub_u32_e32 v3, v5, v3
	v_add_u32_e32 v4, 1, v1
	v_cmp_ge_u32_e32 vcc, v3, v2
	s_nop 1
	v_cndmask_b32_e32 v1, v1, v4, vcc
	v_sub_u32_e32 v4, v3, v2
	v_cndmask_b32_e32 v3, v3, v4, vcc
	v_add_u32_e32 v4, 1, v1
	v_cmp_ge_u32_e32 vcc, v3, v2
	v_add_u32_e32 v3, 1, v5
	s_nop 0
	v_cndmask_b32_e32 v1, v1, v4, vcc
	v_mul_lo_u32 v4, v2, v1
	v_add_u32_e32 v2, v4, v2
	v_cmp_ne_u32_e32 vcc, v3, v2
	s_and_saveexec_b64 s[10:11], vcc
	s_xor_b64 s[10:11], exec, s[10:11]
	s_cbranch_execz .LBB0_415
	s_waitcnt lgkmcnt(0)
	v_mov_b32_e32 v0, 0xcb500
	global_load_dword v0, v0, s[6:7] sc1
	s_add_u32 s20, s6, 0xcb500
	s_addc_u32 s21, s7, 0
	s_waitcnt vmcnt(0)
	v_cmp_eq_u32_e32 vcc, v0, v1
	s_and_saveexec_b64 s[12:13], vcc
	s_cbranch_execz .LBB0_414
	s_add_u32 s14, s6, 0xc8200
	s_addc_u32 s15, s7, 0
	s_mov_b32 s3, 1
	s_mov_b64 s[22:23], 0
	v_mov_b32_e32 v0, 0
	s_branch .LBB0_405

; __device__ __forceinline__ unsigned xb_ld(unsigned* p)              { return __hip_atomic_load(p, __ATOMIC_RELAXED, __HIP_MEMORY_SCOPE_AGENT); }
; __device__ __forceinline__ unsigned xb_add(unsigned* p, unsigned v) { return __hip_atomic_fetch_add(p, v, __ATOMIC_RELAXED, __HIP_MEMORY_SCOPE_AGENT); }
; #define XB_SPIN(cond, bar) do { unsigned _sp = 0; while (cond) { __builtin_amdgcn_s_sleep(1); \
;     if ((++_sp & 255u) == 0u) { if (xb_ld(&(bar)[XB_TMO])) break; if (_sp > XB_SPIN_CAP) { atomicAdd(&(bar)[XB_TMO], 1u); break; } } } } while (0)
; __device__ __forceinline__ void xcd_barrier(const XcdBarrier& b) {
;     ...
;         const unsigned old = xb_add(&bar[XB_XSUB(b.x)], 1u);
;         const unsigned gen = old / nloc;
;         if (old + 1u == (gen + 1u) * nloc) {
;             __builtin_amdgcn_fence(__ATOMIC_RELEASE, "agent");
;             asm volatile("s_waitcnt vmcnt(0)" ::: "memory");
;             const unsigned og = xb_add(&bar[XB_TOP], 1u);
;             const unsigned tg = og / nx;
;             if (og + 1u == (tg + 1u) * nx) xb_add(&bar[XB_TOPGEN], 1u);
;             else XB_SPIN(xb_ld(&bar[XB_TOPGEN]) == tg, bar);
;             __builtin_amdgcn_fence(__ATOMIC_ACQUIRE, "agent");
;             xb_add(&bar[XB_XGEN(b.x)], 1u);
;             asm volatile("s_waitcnt vmcnt(0)" ::: "memory");
;         } else {
;             XB_SPIN(xb_ld(&bar[XB_XGEN(b.x)]) == gen, bar);
.LBB0_865:
	s_or_b64 exec, exec, s[14:15]
	v_cvt_f32_u32_e32 v4, v2
	s_waitcnt vmcnt(0)
	v_readfirstlane_b32 s3, v3
	v_sub_u32_e32 v3, 0, v2
	v_rcp_iflag_f32_e32 v4, v4
	v_add_u32_e32 v5, s3, v1
	v_mul_f32_e32 v4, 0x4f7ffffe, v4
	v_cvt_u32_f32_e32 v4, v4
	v_mul_lo_u32 v1, v3, v4
	v_mul_hi_u32 v1, v4, v1
	v_add_u32_e32 v1, v4, v1
	v_mul_hi_u32 v1, v5, v1
	v_mul_lo_u32 v3, v1, v2
	v_sub_u32_e32 v3, v5, v3
	v_add_u32_e32 v4, 1, v1
	v_cmp_ge_u32_e32 vcc, v3, v2
	s_nop 1
	v_cndmask_b32_e32 v1, v1, v4, vcc
	v_sub_u32_e32 v4, v3, v2
	v_cndmask_b32_e32 v3, v3, v4, vcc
	v_add_u32_e32 v4, 1, v1
	v_cmp_ge_u32_e32 vcc, v3, v2
	v_add_u32_e32 v3, 1, v5
	s_nop 0
	v_cndmask_b32_e32 v1, v1, v4, vcc
	v_mul_lo_u32 v4, v2, v1
	v_add_u32_e32 v2, v4, v2
	v_cmp_ne_u32_e32 vcc, v3, v2
	s_and_saveexec_b64 s[6:7], vcc
	s_xor_b64 s[12:13], exec, s[6:7]
	s_cbranch_execz .LBB0_879
	s_waitcnt lgkmcnt(0)
	v_mov_b32_e32 v0, 0xcb500
	global_load_dword v0, v0, s[8:9] sc1
	s_add_u32 s22, s8, 0xcb500
	s_addc_u32 s23, s9, 0
	s_waitcnt vmcnt(0)
	v_cmp_eq_u32_e32 vcc, v0, v1
	s_and_saveexec_b64 s[14:15], vcc
	s_cbranch_execz .LBB0_878
	s_add_u32 s20, s8, 0xc8200
	s_addc_u32 s21, s9, 0
	s_mov_b32 s3, 1
	s_mov_b64 s[26:27], 0
	v_mov_b32_e32 v0, 0
	s_branch .LBB0_869

; __device__ __forceinline__ unsigned xb_ld(unsigned* p)              { return __hip_atomic_load(p, __ATOMIC_RELAXED, __HIP_MEMORY_SCOPE_AGENT); }
; __device__ __forceinline__ unsigned xb_add(unsigned* p, unsigned v) { return __hip_atomic_fetch_add(p, v, __ATOMIC_RELAXED, __HIP_MEMORY_SCOPE_AGENT); }
; #define XB_SPIN(cond, bar) do { unsigned _sp = 0; while (cond) { __builtin_amdgcn_s_sleep(1); \
;     if ((++_sp & 255u) == 0u) { if (xb_ld(&(bar)[XB_TMO])) break; if (_sp > XB_SPIN_CAP) { atomicAdd(&(bar)[XB_TMO], 1u); break; } } } } while (0)
; __device__ __forceinline__ void xcd_barrier(const XcdBarrier& b) {
;     ...
;         const unsigned old = xb_add(&bar[XB_XSUB(b.x)], 1u);
;         const unsigned gen = old / nloc;
;         if (old + 1u == (gen + 1u) * nloc) {
;             __builtin_amdgcn_fence(__ATOMIC_RELEASE, "agent");
;             asm volatile("s_waitcnt vmcnt(0)" ::: "memory");
;             const unsigned og = xb_add(&bar[XB_TOP], 1u);
;             const unsigned tg = og / nx;
;             if (og + 1u == (tg + 1u) * nx) xb_add(&bar[XB_TOPGEN], 1u);
;             else XB_SPIN(xb_ld(&bar[XB_TOPGEN]) == tg, bar);
;             __builtin_amdgcn_fence(__ATOMIC_ACQUIRE, "agent");
;             xb_add(&bar[XB_XGEN(b.x)], 1u);
;             asm volatile("s_waitcnt vmcnt(0)" ::: "memory");
;         } else {
;             XB_SPIN(xb_ld(&bar[XB_XGEN(b.x)]) == gen, bar);
.LBB0_1006:
	s_or_b64 exec, exec, s[20:21]
	v_cvt_f32_u32_e32 v4, v2
	s_waitcnt vmcnt(0)
	v_readfirstlane_b32 s6, v3
	v_sub_u32_e32 v3, 0, v2
	v_rcp_iflag_f32_e32 v4, v4
	v_add_u32_e32 v5, s6, v1
	v_mul_f32_e32 v4, 0x4f7ffffe, v4
	v_cvt_u32_f32_e32 v4, v4
	v_mul_lo_u32 v1, v3, v4
	v_mul_hi_u32 v1, v4, v1
	v_add_u32_e32 v1, v4, v1
	v_mul_hi_u32 v1, v5, v1
	v_mul_lo_u32 v3, v1, v2
	v_sub_u32_e32 v3, v5, v3
	v_add_u32_e32 v4, 1, v1
	v_cmp_ge_u32_e32 vcc, v3, v2
	s_nop 1
	v_cndmask_b32_e32 v1, v1, v4, vcc
	v_sub_u32_e32 v4, v3, v2
	v_cndmask_b32_e32 v3, v3, v4, vcc
	v_add_u32_e32 v4, 1, v1
	v_cmp_ge_u32_e32 vcc, v3, v2
	v_add_u32_e32 v3, 1, v5
	s_nop 0
	v_cndmask_b32_e32 v1, v1, v4, vcc
	v_mul_lo_u32 v4, v2, v1
	v_add_u32_e32 v2, v4, v2
	v_cmp_ne_u32_e32 vcc, v3, v2
	s_and_saveexec_b64 s[6:7], vcc
	s_xor_b64 s[14:15], exec, s[6:7]
	s_cbranch_execz .LBB0_1020
	s_waitcnt lgkmcnt(0)
	v_mov_b32_e32 v0, 0xcb500
	global_load_dword v0, v0, s[10:11] sc1
	s_add_u32 s26, s10, 0xcb500
	s_addc_u32 s27, s11, 0
	s_waitcnt vmcnt(0)
	v_cmp_eq_u32_e32 vcc, v0, v1
	s_and_saveexec_b64 s[20:21], vcc
	s_cbranch_execz .LBB0_1019
	s_add_u32 s22, s10, 0xc8200
	s_addc_u32 s23, s11, 0
	s_mov_b32 s6, 1
	s_mov_b64 s[36:37], 0
	v_mov_b32_e32 v0, 0
	s_branch .LBB0_1010

; __device__ __forceinline__ unsigned xb_ld(unsigned* p)              { return __hip_atomic_load(p, __ATOMIC_RELAXED, __HIP_MEMORY_SCOPE_AGENT); }
; __device__ __forceinline__ unsigned xb_add(unsigned* p, unsigned v) { return __hip_atomic_fetch_add(p, v, __ATOMIC_RELAXED, __HIP_MEMORY_SCOPE_AGENT); }
; #define XB_SPIN(cond, bar) do { unsigned _sp = 0; while (cond) { __builtin_amdgcn_s_sleep(1); \
;     if ((++_sp & 255u) == 0u) { if (xb_ld(&(bar)[XB_TMO])) break; if (_sp > XB_SPIN_CAP) { atomicAdd(&(bar)[XB_TMO], 1u); break; } } } } while (0)
; __device__ __forceinline__ void xcd_barrier(const XcdBarrier& b) {
;     ...
;         const unsigned old = xb_add(&bar[XB_XSUB(b.x)], 1u);
;         const unsigned gen = old / nloc;
;         if (old + 1u == (gen + 1u) * nloc) {
;             __builtin_amdgcn_fence(__ATOMIC_RELEASE, "agent");
;             asm volatile("s_waitcnt vmcnt(0)" ::: "memory");
;             const unsigned og = xb_add(&bar[XB_TOP], 1u);
;             const unsigned tg = og / nx;
;             if (og + 1u == (tg + 1u) * nx) xb_add(&bar[XB_TOPGEN], 1u);
;             else XB_SPIN(xb_ld(&bar[XB_TOPGEN]) == tg, bar);
;             __builtin_amdgcn_fence(__ATOMIC_ACQUIRE, "agent");
;             xb_add(&bar[XB_XGEN(b.x)], 1u);
;             asm volatile("s_waitcnt vmcnt(0)" ::: "memory");
;         } else {
;             XB_SPIN(xb_ld(&bar[XB_XGEN(b.x)]) == gen, bar);
.LBB0_1212:
	s_or_b64 exec, exec, s[20:21]
	v_cvt_f32_u32_e32 v4, v2
	s_waitcnt vmcnt(0)
	v_readfirstlane_b32 s6, v3
	v_sub_u32_e32 v3, 0, v2
	v_rcp_iflag_f32_e32 v4, v4
	v_add_u32_e32 v5, s6, v1
	v_mul_f32_e32 v4, 0x4f7ffffe, v4
	v_cvt_u32_f32_e32 v4, v4
	v_mul_lo_u32 v1, v3, v4
	v_mul_hi_u32 v1, v4, v1
	v_add_u32_e32 v1, v4, v1
	v_mul_hi_u32 v1, v5, v1
	v_mul_lo_u32 v3, v1, v2
	v_sub_u32_e32 v3, v5, v3
	v_add_u32_e32 v4, 1, v1
	v_cmp_ge_u32_e32 vcc, v3, v2
	s_nop 1
	v_cndmask_b32_e32 v1, v1, v4, vcc
	v_sub_u32_e32 v4, v3, v2
	v_cndmask_b32_e32 v3, v3, v4, vcc
	v_add_u32_e32 v4, 1, v1
	v_cmp_ge_u32_e32 vcc, v3, v2
	v_add_u32_e32 v3, 1, v5
	s_nop 0
	v_cndmask_b32_e32 v1, v1, v4, vcc
	v_mul_lo_u32 v4, v2, v1
	v_add_u32_e32 v2, v4, v2
	v_cmp_ne_u32_e32 vcc, v3, v2
	s_and_saveexec_b64 s[6:7], vcc
	s_xor_b64 s[18:19], exec, s[6:7]
	s_cbranch_execz .LBB0_1226
	s_waitcnt lgkmcnt(0)
	v_mov_b32_e32 v0, 0xcb500
	global_load_dword v0, v0, s[12:13] sc1
	s_add_u32 s26, s12, 0xcb500
	s_addc_u32 s27, s13, 0
	s_waitcnt vmcnt(0)
	v_cmp_eq_u32_e32 vcc, v0, v1
	s_and_saveexec_b64 s[20:21], vcc
	s_cbranch_execz .LBB0_1225
	s_add_u32 s22, s12, 0xc8200
	s_addc_u32 s23, s13, 0
	s_mov_b32 s6, 1
	s_mov_b64 s[36:37], 0
	v_mov_b32_e32 v0, 0
	s_branch .LBB0_1216

; __device__ __forceinline__ unsigned xb_ld(unsigned* p)              { return __hip_atomic_load(p, __ATOMIC_RELAXED, __HIP_MEMORY_SCOPE_AGENT); }
; __device__ __forceinline__ unsigned xb_add(unsigned* p, unsigned v) { return __hip_atomic_fetch_add(p, v, __ATOMIC_RELAXED, __HIP_MEMORY_SCOPE_AGENT); }
; #define XB_SPIN(cond, bar) do { unsigned _sp = 0; while (cond) { __builtin_amdgcn_s_sleep(1); \
;     if ((++_sp & 255u) == 0u) { if (xb_ld(&(bar)[XB_TMO])) break; if (_sp > XB_SPIN_CAP) { atomicAdd(&(bar)[XB_TMO], 1u); break; } } } } while (0)
; __device__ __forceinline__ void xcd_barrier(const XcdBarrier& b) {
;     ...
;         const unsigned old = xb_add(&bar[XB_XSUB(b.x)], 1u);
;         const unsigned gen = old / nloc;
;         if (old + 1u == (gen + 1u) * nloc) {
;             __builtin_amdgcn_fence(__ATOMIC_RELEASE, "agent");
;             asm volatile("s_waitcnt vmcnt(0)" ::: "memory");
;             const unsigned og = xb_add(&bar[XB_TOP], 1u);
;             const unsigned tg = og / nx;
;             if (og + 1u == (tg + 1u) * nx) xb_add(&bar[XB_TOPGEN], 1u);
;             else XB_SPIN(xb_ld(&bar[XB_TOPGEN]) == tg, bar);
;             __builtin_amdgcn_fence(__ATOMIC_ACQUIRE, "agent");
;             xb_add(&bar[XB_XGEN(b.x)], 1u);
;             asm volatile("s_waitcnt vmcnt(0)" ::: "memory");
;         } else {
;             XB_SPIN(xb_ld(&bar[XB_XGEN(b.x)]) == gen, bar);
.LBB0_1288:
	s_or_b64 exec, exec, s[20:21]
	v_cvt_f32_u32_e32 v4, v2
	s_waitcnt vmcnt(0)
	v_readfirstlane_b32 s6, v3
	v_sub_u32_e32 v3, 0, v2
	v_rcp_iflag_f32_e32 v4, v4
	v_add_u32_e32 v5, s6, v1
	v_mul_f32_e32 v4, 0x4f7ffffe, v4
	v_cvt_u32_f32_e32 v4, v4
	v_mul_lo_u32 v1, v3, v4
	v_mul_hi_u32 v1, v4, v1
	v_add_u32_e32 v1, v4, v1
	v_mul_hi_u32 v1, v5, v1
	v_mul_lo_u32 v3, v1, v2
	v_sub_u32_e32 v3, v5, v3
	v_add_u32_e32 v4, 1, v1
	v_cmp_ge_u32_e32 vcc, v3, v2
	s_nop 1
	v_cndmask_b32_e32 v1, v1, v4, vcc
	v_sub_u32_e32 v4, v3, v2
	v_cndmask_b32_e32 v3, v3, v4, vcc
	v_add_u32_e32 v4, 1, v1
	v_cmp_ge_u32_e32 vcc, v3, v2
	v_add_u32_e32 v3, 1, v5
	s_nop 0
	v_cndmask_b32_e32 v1, v1, v4, vcc
	v_mul_lo_u32 v4, v2, v1
	v_add_u32_e32 v2, v4, v2
	v_cmp_ne_u32_e32 vcc, v3, v2
	s_and_saveexec_b64 s[6:7], vcc
	s_xor_b64 s[18:19], exec, s[6:7]
	s_cbranch_execz .LBB0_1302
	s_waitcnt lgkmcnt(0)
	v_mov_b32_e32 v0, 0xcb500
	global_load_dword v0, v0, s[14:15] sc1
	s_add_u32 s26, s14, 0xcb500
	s_addc_u32 s27, s15, 0
	s_waitcnt vmcnt(0)
	v_cmp_eq_u32_e32 vcc, v0, v1
	s_and_saveexec_b64 s[20:21], vcc
	s_cbranch_execz .LBB0_1301
	s_add_u32 s22, s14, 0xc8200
	s_addc_u32 s23, s15, 0
	s_mov_b32 s6, 1
	s_mov_b64 s[36:37], 0
	v_mov_b32_e32 v0, 0
	s_branch .LBB0_1292

; __device__ __forceinline__ unsigned xb_ld(unsigned* p)              { return __hip_atomic_load(p, __ATOMIC_RELAXED, __HIP_MEMORY_SCOPE_AGENT); }
; __device__ __forceinline__ unsigned xb_add(unsigned* p, unsigned v) { return __hip_atomic_fetch_add(p, v, __ATOMIC_RELAXED, __HIP_MEMORY_SCOPE_AGENT); }
; #define XB_SPIN(cond, bar) do { unsigned _sp = 0; while (cond) { __builtin_amdgcn_s_sleep(1); \
;     if ((++_sp & 255u) == 0u) { if (xb_ld(&(bar)[XB_TMO])) break; if (_sp > XB_SPIN_CAP) { atomicAdd(&(bar)[XB_TMO], 1u); break; } } } } while (0)
; __device__ __forceinline__ void xcd_barrier(const XcdBarrier& b) {
;     ...
;         const unsigned old = xb_add(&bar[XB_XSUB(b.x)], 1u);
;         const unsigned gen = old / nloc;
;         if (old + 1u == (gen + 1u) * nloc) {
;             __builtin_amdgcn_fence(__ATOMIC_RELEASE, "agent");
;             asm volatile("s_waitcnt vmcnt(0)" ::: "memory");
;             const unsigned og = xb_add(&bar[XB_TOP], 1u);
;             const unsigned tg = og / nx;
;             if (og + 1u == (tg + 1u) * nx) xb_add(&bar[XB_TOPGEN], 1u);
;             else XB_SPIN(xb_ld(&bar[XB_TOPGEN]) == tg, bar);
;             __builtin_amdgcn_fence(__ATOMIC_ACQUIRE, "agent");
;             xb_add(&bar[XB_XGEN(b.x)], 1u);
;             asm volatile("s_waitcnt vmcnt(0)" ::: "memory");
;         } else {
;             XB_SPIN(xb_ld(&bar[XB_XGEN(b.x)]) == gen, bar);
.LBB0_1508:
	s_or_b64 exec, exec, s[18:19]
	v_cvt_f32_u32_e32 v4, v2
	s_waitcnt vmcnt(0)
	v_readfirstlane_b32 s6, v3
	v_sub_u32_e32 v3, 0, v2
	v_rcp_iflag_f32_e32 v4, v4
	v_add_u32_e32 v5, s6, v1
	v_mul_f32_e32 v4, 0x4f7ffffe, v4
	v_cvt_u32_f32_e32 v4, v4
	v_mul_lo_u32 v1, v3, v4
	v_mul_hi_u32 v1, v4, v1
	v_add_u32_e32 v1, v4, v1
	v_mul_hi_u32 v1, v5, v1
	v_mul_lo_u32 v3, v1, v2
	v_sub_u32_e32 v3, v5, v3
	v_add_u32_e32 v4, 1, v1
	v_cmp_ge_u32_e32 vcc, v3, v2
	s_nop 1
	v_cndmask_b32_e32 v1, v1, v4, vcc
	v_sub_u32_e32 v4, v3, v2
	v_cndmask_b32_e32 v3, v3, v4, vcc
	v_add_u32_e32 v4, 1, v1
	v_cmp_ge_u32_e32 vcc, v3, v2
	v_add_u32_e32 v3, 1, v5
	s_nop 0
	v_cndmask_b32_e32 v1, v1, v4, vcc
	v_mul_lo_u32 v4, v2, v1
	v_add_u32_e32 v2, v4, v2
	v_cmp_ne_u32_e32 vcc, v3, v2
	s_and_saveexec_b64 s[6:7], vcc
	s_xor_b64 s[16:17], exec, s[6:7]
	s_cbranch_execz .LBB0_1522
	s_waitcnt lgkmcnt(0)
	v_mov_b32_e32 v0, 0xcb500
	global_load_dword v0, v0, s[12:13] sc1
	s_add_u32 s22, s12, 0xcb500
	s_addc_u32 s23, s13, 0
	s_waitcnt vmcnt(0)
	v_cmp_eq_u32_e32 vcc, v0, v1
	s_and_saveexec_b64 s[18:19], vcc
	s_cbranch_execz .LBB0_1521
	s_add_u32 s20, s12, 0xc8200
	s_addc_u32 s21, s13, 0
	s_mov_b32 s6, 1
	s_mov_b64 s[26:27], 0
	v_mov_b32_e32 v0, 0
	s_branch .LBB0_1512

; __device__ __forceinline__ unsigned xb_ld(unsigned* p)              { return __hip_atomic_load(p, __ATOMIC_RELAXED, __HIP_MEMORY_SCOPE_AGENT); }
; __device__ __forceinline__ unsigned xb_add(unsigned* p, unsigned v) { return __hip_atomic_fetch_add(p, v, __ATOMIC_RELAXED, __HIP_MEMORY_SCOPE_AGENT); }
; #define XB_SPIN(cond, bar) do { unsigned _sp = 0; while (cond) { __builtin_amdgcn_s_sleep(1); \
;     if ((++_sp & 255u) == 0u) { if (xb_ld(&(bar)[XB_TMO])) break; if (_sp > XB_SPIN_CAP) { atomicAdd(&(bar)[XB_TMO], 1u); break; } } } } while (0)
; __device__ __forceinline__ void xcd_barrier(const XcdBarrier& b) {
;     ...
;         const unsigned old = xb_add(&bar[XB_XSUB(b.x)], 1u);
;         const unsigned gen = old / nloc;
;         if (old + 1u == (gen + 1u) * nloc) {
;             __builtin_amdgcn_fence(__ATOMIC_RELEASE, "agent");
;             asm volatile("s_waitcnt vmcnt(0)" ::: "memory");
;             const unsigned og = xb_add(&bar[XB_TOP], 1u);
;             const unsigned tg = og / nx;
;             if (og + 1u == (tg + 1u) * nx) xb_add(&bar[XB_TOPGEN], 1u);
;             else XB_SPIN(xb_ld(&bar[XB_TOPGEN]) == tg, bar);
;             __builtin_amdgcn_fence(__ATOMIC_ACQUIRE, "agent");
;             xb_add(&bar[XB_XGEN(b.x)], 1u);
;             asm volatile("s_waitcnt vmcnt(0)" ::: "memory");
;         } else {
;             XB_SPIN(xb_ld(&bar[XB_XGEN(b.x)]) == gen, bar);
.LBB0_2116:
	s_or_b64 exec, exec, s[16:17]
	v_cvt_f32_u32_e32 v4, v2
	s_waitcnt vmcnt(0)
	v_readfirstlane_b32 s8, v3
	v_sub_u32_e32 v3, 0, v2
	v_rcp_iflag_f32_e32 v4, v4
	v_add_u32_e32 v5, s8, v1
	v_mul_f32_e32 v4, 0x4f7ffffe, v4
	v_cvt_u32_f32_e32 v4, v4
	v_mul_lo_u32 v1, v3, v4
	v_mul_hi_u32 v1, v4, v1
	v_add_u32_e32 v1, v4, v1
	v_mul_hi_u32 v1, v5, v1
	v_mul_lo_u32 v3, v1, v2
	v_sub_u32_e32 v3, v5, v3
	v_add_u32_e32 v4, 1, v1
	v_cmp_ge_u32_e32 vcc, v3, v2
	s_nop 1
	v_cndmask_b32_e32 v1, v1, v4, vcc
	v_sub_u32_e32 v4, v3, v2
	v_cndmask_b32_e32 v3, v3, v4, vcc
	v_add_u32_e32 v4, 1, v1
	v_cmp_ge_u32_e32 vcc, v3, v2
	v_add_u32_e32 v3, 1, v5
	s_nop 0
	v_cndmask_b32_e32 v1, v1, v4, vcc
	v_mul_lo_u32 v4, v2, v1
	v_add_u32_e32 v2, v4, v2
	v_cmp_ne_u32_e32 vcc, v3, v2
	s_and_saveexec_b64 s[8:9], vcc
	s_xor_b64 s[14:15], exec, s[8:9]
	s_cbranch_execz .LBB0_2130
	s_waitcnt lgkmcnt(0)
	v_mov_b32_e32 v0, 0xcb500
	global_load_dword v0, v0, s[10:11] sc1
	s_add_u32 s20, s10, 0xcb500
	s_addc_u32 s21, s11, 0
	s_waitcnt vmcnt(0)
	v_cmp_eq_u32_e32 vcc, v0, v1
	s_and_saveexec_b64 s[16:17], vcc
	s_cbranch_execz .LBB0_2129
	s_add_u32 s18, s10, 0xc8200
	s_addc_u32 s19, s11, 0
	s_mov_b32 s8, 1
	s_mov_b64 s[22:23], 0
	v_mov_b32_e32 v0, 0
	s_branch .LBB0_2120

; __device__ __forceinline__ unsigned xb_ld(unsigned* p)              { return __hip_atomic_load(p, __ATOMIC_RELAXED, __HIP_MEMORY_SCOPE_AGENT); }
; __device__ __forceinline__ unsigned xb_add(unsigned* p, unsigned v) { return __hip_atomic_fetch_add(p, v, __ATOMIC_RELAXED, __HIP_MEMORY_SCOPE_AGENT); }
; #define XB_SPIN(cond, bar) do { unsigned _sp = 0; while (cond) { __builtin_amdgcn_s_sleep(1); \
;     if ((++_sp & 255u) == 0u) { if (xb_ld(&(bar)[XB_TMO])) break; if (_sp > XB_SPIN_CAP) { atomicAdd(&(bar)[XB_TMO], 1u); break; } } } } while (0)
; __device__ __forceinline__ void xcd_barrier(const XcdBarrier& b) {
;     ...
;         const unsigned old = xb_add(&bar[XB_XSUB(b.x)], 1u);
;         const unsigned gen = old / nloc;
;         if (old + 1u == (gen + 1u) * nloc) {
;             __builtin_amdgcn_fence(__ATOMIC_RELEASE, "agent");
;             asm volatile("s_waitcnt vmcnt(0)" ::: "memory");
;             const unsigned og = xb_add(&bar[XB_TOP], 1u);
;             const unsigned tg = og / nx;
;             if (og + 1u == (tg + 1u) * nx) xb_add(&bar[XB_TOPGEN], 1u);
;             else XB_SPIN(xb_ld(&bar[XB_TOPGEN]) == tg, bar);
;             __builtin_amdgcn_fence(__ATOMIC_ACQUIRE, "agent");
;             xb_add(&bar[XB_XGEN(b.x)], 1u);
;             asm volatile("s_waitcnt vmcnt(0)" ::: "memory");
;         } else {
;             XB_SPIN(xb_ld(&bar[XB_XGEN(b.x)]) == gen, bar);
.LBB0_2217:
	s_or_b64 exec, exec, s[14:15]
	v_cvt_f32_u32_e32 v4, v2
	s_waitcnt vmcnt(0)
	v_readfirstlane_b32 s12, v3
	v_sub_u32_e32 v3, 0, v2
	v_rcp_iflag_f32_e32 v4, v4
	v_add_u32_e32 v5, s12, v1
	v_mul_f32_e32 v4, 0x4f7ffffe, v4
	v_cvt_u32_f32_e32 v4, v4
	v_mul_lo_u32 v1, v3, v4
	v_mul_hi_u32 v1, v4, v1
	v_add_u32_e32 v1, v4, v1
	v_mul_hi_u32 v1, v5, v1
	v_mul_lo_u32 v3, v1, v2
	v_sub_u32_e32 v3, v5, v3
	v_add_u32_e32 v4, 1, v1
	v_cmp_ge_u32_e32 vcc, v3, v2
	s_nop 1
	v_cndmask_b32_e32 v1, v1, v4, vcc
	v_sub_u32_e32 v4, v3, v2
	v_cndmask_b32_e32 v3, v3, v4, vcc
	v_add_u32_e32 v4, 1, v1
	v_cmp_ge_u32_e32 vcc, v3, v2
	v_add_u32_e32 v3, 1, v5
	s_nop 0
	v_cndmask_b32_e32 v1, v1, v4, vcc
	v_mul_lo_u32 v4, v2, v1
	v_add_u32_e32 v2, v4, v2
	v_cmp_ne_u32_e32 vcc, v3, v2
	s_and_saveexec_b64 s[12:13], vcc
	s_xor_b64 s[12:13], exec, s[12:13]
	s_cbranch_execz .LBB0_2231
	s_waitcnt lgkmcnt(0)
	v_mov_b32_e32 v0, 0xcb500
	global_load_dword v0, v0, s[8:9] sc1
	s_add_u32 s18, s8, 0xcb500
	s_addc_u32 s19, s9, 0
	s_waitcnt vmcnt(0)
	v_cmp_eq_u32_e32 vcc, v0, v1
	s_and_saveexec_b64 s[14:15], vcc
	s_cbranch_execz .LBB0_2230
	s_add_u32 s16, s8, 0xc8200
	s_addc_u32 s17, s9, 0
	s_mov_b32 s29, 1
	s_mov_b64 s[20:21], 0
	v_mov_b32_e32 v0, 0
	s_branch .LBB0_2221
